# scan pass B: all 32 loads of each 8-step batch issued up front (per-workgroup rotated order) instead of serialised behind the per-step stores
# baseline (speedup 1.0000x reference)
.LBB0_1021:
	v_lshl_add_u64 v[140:141], v[134:135], 0, v[188:189]
	v_add_co_u32_e32 v142, vcc, 0x23a00000, v140
	s_mov_b32 s1, 0x1ba01000
	s_nop 0
	v_addc_co_u32_e32 v143, vcc, 0, v141, vcc
	v_add_co_u32_e32 v142, vcc, 0x23a01000, v140
	s_mov_b64 s[6:7], 0x8000
	s_nop 0
	v_addc_co_u32_e32 v143, vcc, 0, v141, vcc
	v_lshl_add_u64 v[142:143], v[132:133], 0, v[188:189]
	s_mov_b32 s99, 0
	s_and_b32 s100, s97, 7
	s_cmp_eq_u32 s100, 0
	s_cbranch_scc1 .Lsb_rot0
	s_cmp_eq_u32 s100, 1
	s_cbranch_scc1 .Lsb_rot1
	s_cmp_eq_u32 s100, 2
	s_cbranch_scc1 .Lsb_rot2
	s_cmp_eq_u32 s100, 3
	s_cbranch_scc1 .Lsb_rot3
	s_cmp_eq_u32 s100, 4
	s_cbranch_scc1 .Lsb_rot4
	s_cmp_eq_u32 s100, 5
	s_cbranch_scc1 .Lsb_rot5
	s_cmp_eq_u32 s100, 6
	s_cbranch_scc1 .Lsb_rot6
.Lsb_rot7:
	s_mov_b32 s98, 0x23a0e800
	v_lshl_add_u64 v[144:145], v[140:141], 0, s[98:99]
	global_load_dwordx2 v[226:227], v[144:145], off offset:-2048
	global_load_dwordx2 v[232:233], v[144:145], off offset:2048
	s_mov_b32 s98, 0x1fa06800
	v_lshl_add_u64 v[148:149], v[142:143], 0, s[98:99]
	global_load_dwordx2 v[234:235], v[148:149], off offset:2048
	s_mov_b32 s98, 0x1ba0f000
	v_lshl_add_u64 v[146:147], v[140:141], 0, s[98:99]
	global_load_dwordx2 v[238:239], v[146:147], off
	s_mov_b32 s98, 0x23a00800
	v_lshl_add_u64 v[144:145], v[140:141], 0, s[98:99]
	global_load_dwordx2 v[162:163], v[144:145], off offset:-2048
	global_load_dwordx2 v[164:165], v[144:145], off offset:2048
	s_mov_b32 s98, 0x1fa00800
	v_lshl_add_u64 v[148:149], v[142:143], 0, s[98:99]
	global_load_dwordx2 v[166:167], v[148:149], off offset:-2048
	s_mov_b32 s98, 0x1ba01000
	v_lshl_add_u64 v[146:147], v[140:141], 0, s[98:99]
	global_load_dwordx2 v[168:169], v[146:147], off
	s_mov_b32 s98, 0x23a02800
	v_lshl_add_u64 v[144:145], v[140:141], 0, s[98:99]
	global_load_dwordx2 v[170:171], v[144:145], off offset:-2048
	global_load_dwordx2 v[172:173], v[144:145], off offset:2048
	s_mov_b32 s98, 0x1fa00800
	v_lshl_add_u64 v[148:149], v[142:143], 0, s[98:99]
	global_load_dwordx2 v[174:175], v[148:149], off offset:2048
	s_mov_b32 s98, 0x1ba03000
	v_lshl_add_u64 v[146:147], v[140:141], 0, s[98:99]
	global_load_dwordx2 v[176:177], v[146:147], off
	s_mov_b32 s98, 0x23a04800
	v_lshl_add_u64 v[144:145], v[140:141], 0, s[98:99]
	global_load_dwordx2 v[178:179], v[144:145], off offset:-2048
	global_load_dwordx2 v[182:183], v[144:145], off offset:2048
	s_mov_b32 s98, 0x1fa02800
	v_lshl_add_u64 v[148:149], v[142:143], 0, s[98:99]
	global_load_dwordx2 v[184:185], v[148:149], off offset:-2048
	s_mov_b32 s98, 0x1ba05000
	v_lshl_add_u64 v[146:147], v[140:141], 0, s[98:99]
	global_load_dwordx2 v[186:187], v[146:147], off
	s_mov_b32 s98, 0x23a06800
	v_lshl_add_u64 v[144:145], v[140:141], 0, s[98:99]
	global_load_dwordx2 v[190:191], v[144:145], off offset:-2048
	global_load_dwordx2 v[194:195], v[144:145], off offset:2048
	s_mov_b32 s98, 0x1fa02800
	v_lshl_add_u64 v[148:149], v[142:143], 0, s[98:99]
	global_load_dwordx2 v[196:197], v[148:149], off offset:2048
	s_mov_b32 s98, 0x1ba07000
	v_lshl_add_u64 v[146:147], v[140:141], 0, s[98:99]
	global_load_dwordx2 v[198:199], v[146:147], off
	s_mov_b32 s98, 0x23a08800
	v_lshl_add_u64 v[144:145], v[140:141], 0, s[98:99]
	global_load_dwordx2 v[200:201], v[144:145], off offset:-2048
	global_load_dwordx2 v[202:203], v[144:145], off offset:2048
	s_mov_b32 s98, 0x1fa04800
	v_lshl_add_u64 v[148:149], v[142:143], 0, s[98:99]
	global_load_dwordx2 v[204:205], v[148:149], off offset:-2048
	s_mov_b32 s98, 0x1ba09000
	v_lshl_add_u64 v[146:147], v[140:141], 0, s[98:99]
	global_load_dwordx2 v[206:207], v[146:147], off
	s_mov_b32 s98, 0x23a0a800
	v_lshl_add_u64 v[144:145], v[140:141], 0, s[98:99]
	global_load_dwordx2 v[208:209], v[144:145], off offset:-2048
	global_load_dwordx2 v[210:211], v[144:145], off offset:2048
	s_mov_b32 s98, 0x1fa04800
	v_lshl_add_u64 v[148:149], v[142:143], 0, s[98:99]
	global_load_dwordx2 v[212:213], v[148:149], off offset:2048
	s_mov_b32 s98, 0x1ba0b000
	v_lshl_add_u64 v[146:147], v[140:141], 0, s[98:99]
	global_load_dwordx2 v[214:215], v[146:147], off
	s_mov_b32 s98, 0x23a0c800
	v_lshl_add_u64 v[144:145], v[140:141], 0, s[98:99]
	global_load_dwordx2 v[216:217], v[144:145], off offset:-2048
	global_load_dwordx2 v[218:219], v[144:145], off offset:2048
	s_mov_b32 s98, 0x1fa06800
	v_lshl_add_u64 v[148:149], v[142:143], 0, s[98:99]
	global_load_dwordx2 v[222:223], v[148:149], off offset:-2048
	s_mov_b32 s98, 0x1ba0d000
	v_lshl_add_u64 v[146:147], v[140:141], 0, s[98:99]
	global_load_dwordx2 v[224:225], v[146:147], off
	s_branch .Lsb_join
.Lsb_rot0:
	s_mov_b32 s98, 0x23a00800
	v_lshl_add_u64 v[144:145], v[140:141], 0, s[98:99]
	global_load_dwordx2 v[162:163], v[144:145], off offset:-2048
	global_load_dwordx2 v[164:165], v[144:145], off offset:2048
	s_mov_b32 s98, 0x1fa00800
	v_lshl_add_u64 v[148:149], v[142:143], 0, s[98:99]
	global_load_dwordx2 v[166:167], v[148:149], off offset:-2048
	s_mov_b32 s98, 0x1ba01000
	v_lshl_add_u64 v[146:147], v[140:141], 0, s[98:99]
	global_load_dwordx2 v[168:169], v[146:147], off
	s_mov_b32 s98, 0x23a02800
	v_lshl_add_u64 v[144:145], v[140:141], 0, s[98:99]
	global_load_dwordx2 v[170:171], v[144:145], off offset:-2048
	global_load_dwordx2 v[172:173], v[144:145], off offset:2048
	s_mov_b32 s98, 0x1fa00800
	v_lshl_add_u64 v[148:149], v[142:143], 0, s[98:99]
	global_load_dwordx2 v[174:175], v[148:149], off offset:2048
	s_mov_b32 s98, 0x1ba03000
	v_lshl_add_u64 v[146:147], v[140:141], 0, s[98:99]
	global_load_dwordx2 v[176:177], v[146:147], off
	s_mov_b32 s98, 0x23a04800
	v_lshl_add_u64 v[144:145], v[140:141], 0, s[98:99]
	global_load_dwordx2 v[178:179], v[144:145], off offset:-2048
	global_load_dwordx2 v[182:183], v[144:145], off offset:2048
	s_mov_b32 s98, 0x1fa02800
	v_lshl_add_u64 v[148:149], v[142:143], 0, s[98:99]
	global_load_dwordx2 v[184:185], v[148:149], off offset:-2048
	s_mov_b32 s98, 0x1ba05000
	v_lshl_add_u64 v[146:147], v[140:141], 0, s[98:99]
	global_load_dwordx2 v[186:187], v[146:147], off
	s_mov_b32 s98, 0x23a06800
	v_lshl_add_u64 v[144:145], v[140:141], 0, s[98:99]
	global_load_dwordx2 v[190:191], v[144:145], off offset:-2048
	global_load_dwordx2 v[194:195], v[144:145], off offset:2048
	s_mov_b32 s98, 0x1fa02800
	v_lshl_add_u64 v[148:149], v[142:143], 0, s[98:99]
	global_load_dwordx2 v[196:197], v[148:149], off offset:2048
	s_mov_b32 s98, 0x1ba07000
	v_lshl_add_u64 v[146:147], v[140:141], 0, s[98:99]
	global_load_dwordx2 v[198:199], v[146:147], off
	s_mov_b32 s98, 0x23a08800
	v_lshl_add_u64 v[144:145], v[140:141], 0, s[98:99]
	global_load_dwordx2 v[200:201], v[144:145], off offset:-2048
	global_load_dwordx2 v[202:203], v[144:145], off offset:2048
	s_mov_b32 s98, 0x1fa04800
	v_lshl_add_u64 v[148:149], v[142:143], 0, s[98:99]
	global_load_dwordx2 v[204:205], v[148:149], off offset:-2048
	s_mov_b32 s98, 0x1ba09000
	v_lshl_add_u64 v[146:147], v[140:141], 0, s[98:99]
	global_load_dwordx2 v[206:207], v[146:147], off
	s_mov_b32 s98, 0x23a0a800
	v_lshl_add_u64 v[144:145], v[140:141], 0, s[98:99]
	global_load_dwordx2 v[208:209], v[144:145], off offset:-2048
	global_load_dwordx2 v[210:211], v[144:145], off offset:2048
	s_mov_b32 s98, 0x1fa04800
	v_lshl_add_u64 v[148:149], v[142:143], 0, s[98:99]
	global_load_dwordx2 v[212:213], v[148:149], off offset:2048
	s_mov_b32 s98, 0x1ba0b000
	v_lshl_add_u64 v[146:147], v[140:141], 0, s[98:99]
	global_load_dwordx2 v[214:215], v[146:147], off
	s_mov_b32 s98, 0x23a0c800
	v_lshl_add_u64 v[144:145], v[140:141], 0, s[98:99]
	global_load_dwordx2 v[216:217], v[144:145], off offset:-2048
	global_load_dwordx2 v[218:219], v[144:145], off offset:2048
	s_mov_b32 s98, 0x1fa06800
	v_lshl_add_u64 v[148:149], v[142:143], 0, s[98:99]
	global_load_dwordx2 v[222:223], v[148:149], off offset:-2048
	s_mov_b32 s98, 0x1ba0d000
	v_lshl_add_u64 v[146:147], v[140:141], 0, s[98:99]
	global_load_dwordx2 v[224:225], v[146:147], off
	s_mov_b32 s98, 0x23a0e800
	v_lshl_add_u64 v[144:145], v[140:141], 0, s[98:99]
	global_load_dwordx2 v[226:227], v[144:145], off offset:-2048
	global_load_dwordx2 v[232:233], v[144:145], off offset:2048
	s_mov_b32 s98, 0x1fa06800
	v_lshl_add_u64 v[148:149], v[142:143], 0, s[98:99]
	global_load_dwordx2 v[234:235], v[148:149], off offset:2048
	s_mov_b32 s98, 0x1ba0f000
	v_lshl_add_u64 v[146:147], v[140:141], 0, s[98:99]
	global_load_dwordx2 v[238:239], v[146:147], off
	s_branch .Lsb_join
.Lsb_rot1:
	s_mov_b32 s98, 0x23a02800
	v_lshl_add_u64 v[144:145], v[140:141], 0, s[98:99]
	global_load_dwordx2 v[170:171], v[144:145], off offset:-2048
	global_load_dwordx2 v[172:173], v[144:145], off offset:2048
	s_mov_b32 s98, 0x1fa00800
	v_lshl_add_u64 v[148:149], v[142:143], 0, s[98:99]
	global_load_dwordx2 v[174:175], v[148:149], off offset:2048
	s_mov_b32 s98, 0x1ba03000
	v_lshl_add_u64 v[146:147], v[140:141], 0, s[98:99]
	global_load_dwordx2 v[176:177], v[146:147], off
	s_mov_b32 s98, 0x23a04800
	v_lshl_add_u64 v[144:145], v[140:141], 0, s[98:99]
	global_load_dwordx2 v[178:179], v[144:145], off offset:-2048
	global_load_dwordx2 v[182:183], v[144:145], off offset:2048
	s_mov_b32 s98, 0x1fa02800
	v_lshl_add_u64 v[148:149], v[142:143], 0, s[98:99]
	global_load_dwordx2 v[184:185], v[148:149], off offset:-2048
	s_mov_b32 s98, 0x1ba05000
	v_lshl_add_u64 v[146:147], v[140:141], 0, s[98:99]
	global_load_dwordx2 v[186:187], v[146:147], off
	s_mov_b32 s98, 0x23a06800
	v_lshl_add_u64 v[144:145], v[140:141], 0, s[98:99]
	global_load_dwordx2 v[190:191], v[144:145], off offset:-2048
	global_load_dwordx2 v[194:195], v[144:145], off offset:2048
	s_mov_b32 s98, 0x1fa02800
	v_lshl_add_u64 v[148:149], v[142:143], 0, s[98:99]
	global_load_dwordx2 v[196:197], v[148:149], off offset:2048
	s_mov_b32 s98, 0x1ba07000
	v_lshl_add_u64 v[146:147], v[140:141], 0, s[98:99]
	global_load_dwordx2 v[198:199], v[146:147], off
	s_mov_b32 s98, 0x23a08800
	v_lshl_add_u64 v[144:145], v[140:141], 0, s[98:99]
	global_load_dwordx2 v[200:201], v[144:145], off offset:-2048
	global_load_dwordx2 v[202:203], v[144:145], off offset:2048
	s_mov_b32 s98, 0x1fa04800
	v_lshl_add_u64 v[148:149], v[142:143], 0, s[98:99]
	global_load_dwordx2 v[204:205], v[148:149], off offset:-2048
	s_mov_b32 s98, 0x1ba09000
	v_lshl_add_u64 v[146:147], v[140:141], 0, s[98:99]
	global_load_dwordx2 v[206:207], v[146:147], off
	s_mov_b32 s98, 0x23a0a800
	v_lshl_add_u64 v[144:145], v[140:141], 0, s[98:99]
	global_load_dwordx2 v[208:209], v[144:145], off offset:-2048
	global_load_dwordx2 v[210:211], v[144:145], off offset:2048
	s_mov_b32 s98, 0x1fa04800
	v_lshl_add_u64 v[148:149], v[142:143], 0, s[98:99]
	global_load_dwordx2 v[212:213], v[148:149], off offset:2048
	s_mov_b32 s98, 0x1ba0b000
	v_lshl_add_u64 v[146:147], v[140:141], 0, s[98:99]
	global_load_dwordx2 v[214:215], v[146:147], off
	s_mov_b32 s98, 0x23a0c800
	v_lshl_add_u64 v[144:145], v[140:141], 0, s[98:99]
	global_load_dwordx2 v[216:217], v[144:145], off offset:-2048
	global_load_dwordx2 v[218:219], v[144:145], off offset:2048
	s_mov_b32 s98, 0x1fa06800
	v_lshl_add_u64 v[148:149], v[142:143], 0, s[98:99]
	global_load_dwordx2 v[222:223], v[148:149], off offset:-2048
	s_mov_b32 s98, 0x1ba0d000
	v_lshl_add_u64 v[146:147], v[140:141], 0, s[98:99]
	global_load_dwordx2 v[224:225], v[146:147], off
	s_mov_b32 s98, 0x23a0e800
	v_lshl_add_u64 v[144:145], v[140:141], 0, s[98:99]
	global_load_dwordx2 v[226:227], v[144:145], off offset:-2048
	global_load_dwordx2 v[232:233], v[144:145], off offset:2048
	s_mov_b32 s98, 0x1fa06800
	v_lshl_add_u64 v[148:149], v[142:143], 0, s[98:99]
	global_load_dwordx2 v[234:235], v[148:149], off offset:2048
	s_mov_b32 s98, 0x1ba0f000
	v_lshl_add_u64 v[146:147], v[140:141], 0, s[98:99]
	global_load_dwordx2 v[238:239], v[146:147], off
	s_mov_b32 s98, 0x23a00800
	v_lshl_add_u64 v[144:145], v[140:141], 0, s[98:99]
	global_load_dwordx2 v[162:163], v[144:145], off offset:-2048
	global_load_dwordx2 v[164:165], v[144:145], off offset:2048
	s_mov_b32 s98, 0x1fa00800
	v_lshl_add_u64 v[148:149], v[142:143], 0, s[98:99]
	global_load_dwordx2 v[166:167], v[148:149], off offset:-2048
	s_mov_b32 s98, 0x1ba01000
	v_lshl_add_u64 v[146:147], v[140:141], 0, s[98:99]
	global_load_dwordx2 v[168:169], v[146:147], off
	s_branch .Lsb_join
.Lsb_rot2:
	s_mov_b32 s98, 0x23a04800
	v_lshl_add_u64 v[144:145], v[140:141], 0, s[98:99]
	global_load_dwordx2 v[178:179], v[144:145], off offset:-2048
	global_load_dwordx2 v[182:183], v[144:145], off offset:2048
	s_mov_b32 s98, 0x1fa02800
	v_lshl_add_u64 v[148:149], v[142:143], 0, s[98:99]
	global_load_dwordx2 v[184:185], v[148:149], off offset:-2048
	s_mov_b32 s98, 0x1ba05000
	v_lshl_add_u64 v[146:147], v[140:141], 0, s[98:99]
	global_load_dwordx2 v[186:187], v[146:147], off
	s_mov_b32 s98, 0x23a06800
	v_lshl_add_u64 v[144:145], v[140:141], 0, s[98:99]
	global_load_dwordx2 v[190:191], v[144:145], off offset:-2048
	global_load_dwordx2 v[194:195], v[144:145], off offset:2048
	s_mov_b32 s98, 0x1fa02800
	v_lshl_add_u64 v[148:149], v[142:143], 0, s[98:99]
	global_load_dwordx2 v[196:197], v[148:149], off offset:2048
	s_mov_b32 s98, 0x1ba07000
	v_lshl_add_u64 v[146:147], v[140:141], 0, s[98:99]
	global_load_dwordx2 v[198:199], v[146:147], off
	s_mov_b32 s98, 0x23a08800
	v_lshl_add_u64 v[144:145], v[140:141], 0, s[98:99]
	global_load_dwordx2 v[200:201], v[144:145], off offset:-2048
	global_load_dwordx2 v[202:203], v[144:145], off offset:2048
	s_mov_b32 s98, 0x1fa04800
	v_lshl_add_u64 v[148:149], v[142:143], 0, s[98:99]
	global_load_dwordx2 v[204:205], v[148:149], off offset:-2048
	s_mov_b32 s98, 0x1ba09000
	v_lshl_add_u64 v[146:147], v[140:141], 0, s[98:99]
	global_load_dwordx2 v[206:207], v[146:147], off
	s_mov_b32 s98, 0x23a0a800
	v_lshl_add_u64 v[144:145], v[140:141], 0, s[98:99]
	global_load_dwordx2 v[208:209], v[144:145], off offset:-2048
	global_load_dwordx2 v[210:211], v[144:145], off offset:2048
	s_mov_b32 s98, 0x1fa04800
	v_lshl_add_u64 v[148:149], v[142:143], 0, s[98:99]
	global_load_dwordx2 v[212:213], v[148:149], off offset:2048
	s_mov_b32 s98, 0x1ba0b000
	v_lshl_add_u64 v[146:147], v[140:141], 0, s[98:99]
	global_load_dwordx2 v[214:215], v[146:147], off
	s_mov_b32 s98, 0x23a0c800
	v_lshl_add_u64 v[144:145], v[140:141], 0, s[98:99]
	global_load_dwordx2 v[216:217], v[144:145], off offset:-2048
	global_load_dwordx2 v[218:219], v[144:145], off offset:2048
	s_mov_b32 s98, 0x1fa06800
	v_lshl_add_u64 v[148:149], v[142:143], 0, s[98:99]
	global_load_dwordx2 v[222:223], v[148:149], off offset:-2048
	s_mov_b32 s98, 0x1ba0d000
	v_lshl_add_u64 v[146:147], v[140:141], 0, s[98:99]
	global_load_dwordx2 v[224:225], v[146:147], off
	s_mov_b32 s98, 0x23a0e800
	v_lshl_add_u64 v[144:145], v[140:141], 0, s[98:99]
	global_load_dwordx2 v[226:227], v[144:145], off offset:-2048
	global_load_dwordx2 v[232:233], v[144:145], off offset:2048
	s_mov_b32 s98, 0x1fa06800
	v_lshl_add_u64 v[148:149], v[142:143], 0, s[98:99]
	global_load_dwordx2 v[234:235], v[148:149], off offset:2048
	s_mov_b32 s98, 0x1ba0f000
	v_lshl_add_u64 v[146:147], v[140:141], 0, s[98:99]
	global_load_dwordx2 v[238:239], v[146:147], off
	s_mov_b32 s98, 0x23a00800
	v_lshl_add_u64 v[144:145], v[140:141], 0, s[98:99]
	global_load_dwordx2 v[162:163], v[144:145], off offset:-2048
	global_load_dwordx2 v[164:165], v[144:145], off offset:2048
	s_mov_b32 s98, 0x1fa00800
	v_lshl_add_u64 v[148:149], v[142:143], 0, s[98:99]
	global_load_dwordx2 v[166:167], v[148:149], off offset:-2048
	s_mov_b32 s98, 0x1ba01000
	v_lshl_add_u64 v[146:147], v[140:141], 0, s[98:99]
	global_load_dwordx2 v[168:169], v[146:147], off
	s_mov_b32 s98, 0x23a02800
	v_lshl_add_u64 v[144:145], v[140:141], 0, s[98:99]
	global_load_dwordx2 v[170:171], v[144:145], off offset:-2048
	global_load_dwordx2 v[172:173], v[144:145], off offset:2048
	s_mov_b32 s98, 0x1fa00800
	v_lshl_add_u64 v[148:149], v[142:143], 0, s[98:99]
	global_load_dwordx2 v[174:175], v[148:149], off offset:2048
	s_mov_b32 s98, 0x1ba03000
	v_lshl_add_u64 v[146:147], v[140:141], 0, s[98:99]
	global_load_dwordx2 v[176:177], v[146:147], off
	s_branch .Lsb_join
.Lsb_rot3:
	s_mov_b32 s98, 0x23a06800
	v_lshl_add_u64 v[144:145], v[140:141], 0, s[98:99]
	global_load_dwordx2 v[190:191], v[144:145], off offset:-2048
	global_load_dwordx2 v[194:195], v[144:145], off offset:2048
	s_mov_b32 s98, 0x1fa02800
	v_lshl_add_u64 v[148:149], v[142:143], 0, s[98:99]
	global_load_dwordx2 v[196:197], v[148:149], off offset:2048
	s_mov_b32 s98, 0x1ba07000
	v_lshl_add_u64 v[146:147], v[140:141], 0, s[98:99]
	global_load_dwordx2 v[198:199], v[146:147], off
	s_mov_b32 s98, 0x23a08800
	v_lshl_add_u64 v[144:145], v[140:141], 0, s[98:99]
	global_load_dwordx2 v[200:201], v[144:145], off offset:-2048
	global_load_dwordx2 v[202:203], v[144:145], off offset:2048
	s_mov_b32 s98, 0x1fa04800
	v_lshl_add_u64 v[148:149], v[142:143], 0, s[98:99]
	global_load_dwordx2 v[204:205], v[148:149], off offset:-2048
	s_mov_b32 s98, 0x1ba09000
	v_lshl_add_u64 v[146:147], v[140:141], 0, s[98:99]
	global_load_dwordx2 v[206:207], v[146:147], off
	s_mov_b32 s98, 0x23a0a800
	v_lshl_add_u64 v[144:145], v[140:141], 0, s[98:99]
	global_load_dwordx2 v[208:209], v[144:145], off offset:-2048
	global_load_dwordx2 v[210:211], v[144:145], off offset:2048
	s_mov_b32 s98, 0x1fa04800
	v_lshl_add_u64 v[148:149], v[142:143], 0, s[98:99]
	global_load_dwordx2 v[212:213], v[148:149], off offset:2048
	s_mov_b32 s98, 0x1ba0b000
	v_lshl_add_u64 v[146:147], v[140:141], 0, s[98:99]
	global_load_dwordx2 v[214:215], v[146:147], off
	s_mov_b32 s98, 0x23a0c800
	v_lshl_add_u64 v[144:145], v[140:141], 0, s[98:99]
	global_load_dwordx2 v[216:217], v[144:145], off offset:-2048
	global_load_dwordx2 v[218:219], v[144:145], off offset:2048
	s_mov_b32 s98, 0x1fa06800
	v_lshl_add_u64 v[148:149], v[142:143], 0, s[98:99]
	global_load_dwordx2 v[222:223], v[148:149], off offset:-2048
	s_mov_b32 s98, 0x1ba0d000
	v_lshl_add_u64 v[146:147], v[140:141], 0, s[98:99]
	global_load_dwordx2 v[224:225], v[146:147], off
	s_mov_b32 s98, 0x23a0e800
	v_lshl_add_u64 v[144:145], v[140:141], 0, s[98:99]
	global_load_dwordx2 v[226:227], v[144:145], off offset:-2048
	global_load_dwordx2 v[232:233], v[144:145], off offset:2048
	s_mov_b32 s98, 0x1fa06800
	v_lshl_add_u64 v[148:149], v[142:143], 0, s[98:99]
	global_load_dwordx2 v[234:235], v[148:149], off offset:2048
	s_mov_b32 s98, 0x1ba0f000
	v_lshl_add_u64 v[146:147], v[140:141], 0, s[98:99]
	global_load_dwordx2 v[238:239], v[146:147], off
	s_mov_b32 s98, 0x23a00800
	v_lshl_add_u64 v[144:145], v[140:141], 0, s[98:99]
	global_load_dwordx2 v[162:163], v[144:145], off offset:-2048
	global_load_dwordx2 v[164:165], v[144:145], off offset:2048
	s_mov_b32 s98, 0x1fa00800
	v_lshl_add_u64 v[148:149], v[142:143], 0, s[98:99]
	global_load_dwordx2 v[166:167], v[148:149], off offset:-2048
	s_mov_b32 s98, 0x1ba01000
	v_lshl_add_u64 v[146:147], v[140:141], 0, s[98:99]
	global_load_dwordx2 v[168:169], v[146:147], off
	s_mov_b32 s98, 0x23a02800
	v_lshl_add_u64 v[144:145], v[140:141], 0, s[98:99]
	global_load_dwordx2 v[170:171], v[144:145], off offset:-2048
	global_load_dwordx2 v[172:173], v[144:145], off offset:2048
	s_mov_b32 s98, 0x1fa00800
	v_lshl_add_u64 v[148:149], v[142:143], 0, s[98:99]
	global_load_dwordx2 v[174:175], v[148:149], off offset:2048
	s_mov_b32 s98, 0x1ba03000
	v_lshl_add_u64 v[146:147], v[140:141], 0, s[98:99]
	global_load_dwordx2 v[176:177], v[146:147], off
	s_mov_b32 s98, 0x23a04800
	v_lshl_add_u64 v[144:145], v[140:141], 0, s[98:99]
	global_load_dwordx2 v[178:179], v[144:145], off offset:-2048
	global_load_dwordx2 v[182:183], v[144:145], off offset:2048
	s_mov_b32 s98, 0x1fa02800
	v_lshl_add_u64 v[148:149], v[142:143], 0, s[98:99]
	global_load_dwordx2 v[184:185], v[148:149], off offset:-2048
	s_mov_b32 s98, 0x1ba05000
	v_lshl_add_u64 v[146:147], v[140:141], 0, s[98:99]
	global_load_dwordx2 v[186:187], v[146:147], off
	s_branch .Lsb_join
.Lsb_rot4:
	s_mov_b32 s98, 0x23a08800
	v_lshl_add_u64 v[144:145], v[140:141], 0, s[98:99]
	global_load_dwordx2 v[200:201], v[144:145], off offset:-2048
	global_load_dwordx2 v[202:203], v[144:145], off offset:2048
	s_mov_b32 s98, 0x1fa04800
	v_lshl_add_u64 v[148:149], v[142:143], 0, s[98:99]
	global_load_dwordx2 v[204:205], v[148:149], off offset:-2048
	s_mov_b32 s98, 0x1ba09000
	v_lshl_add_u64 v[146:147], v[140:141], 0, s[98:99]
	global_load_dwordx2 v[206:207], v[146:147], off
	s_mov_b32 s98, 0x23a0a800
	v_lshl_add_u64 v[144:145], v[140:141], 0, s[98:99]
	global_load_dwordx2 v[208:209], v[144:145], off offset:-2048
	global_load_dwordx2 v[210:211], v[144:145], off offset:2048
	s_mov_b32 s98, 0x1fa04800
	v_lshl_add_u64 v[148:149], v[142:143], 0, s[98:99]
	global_load_dwordx2 v[212:213], v[148:149], off offset:2048
	s_mov_b32 s98, 0x1ba0b000
	v_lshl_add_u64 v[146:147], v[140:141], 0, s[98:99]
	global_load_dwordx2 v[214:215], v[146:147], off
	s_mov_b32 s98, 0x23a0c800
	v_lshl_add_u64 v[144:145], v[140:141], 0, s[98:99]
	global_load_dwordx2 v[216:217], v[144:145], off offset:-2048
	global_load_dwordx2 v[218:219], v[144:145], off offset:2048
	s_mov_b32 s98, 0x1fa06800
	v_lshl_add_u64 v[148:149], v[142:143], 0, s[98:99]
	global_load_dwordx2 v[222:223], v[148:149], off offset:-2048
	s_mov_b32 s98, 0x1ba0d000
	v_lshl_add_u64 v[146:147], v[140:141], 0, s[98:99]
	global_load_dwordx2 v[224:225], v[146:147], off
	s_mov_b32 s98, 0x23a0e800
	v_lshl_add_u64 v[144:145], v[140:141], 0, s[98:99]
	global_load_dwordx2 v[226:227], v[144:145], off offset:-2048
	global_load_dwordx2 v[232:233], v[144:145], off offset:2048
	s_mov_b32 s98, 0x1fa06800
	v_lshl_add_u64 v[148:149], v[142:143], 0, s[98:99]
	global_load_dwordx2 v[234:235], v[148:149], off offset:2048
	s_mov_b32 s98, 0x1ba0f000
	v_lshl_add_u64 v[146:147], v[140:141], 0, s[98:99]
	global_load_dwordx2 v[238:239], v[146:147], off
	s_mov_b32 s98, 0x23a00800
	v_lshl_add_u64 v[144:145], v[140:141], 0, s[98:99]
	global_load_dwordx2 v[162:163], v[144:145], off offset:-2048
	global_load_dwordx2 v[164:165], v[144:145], off offset:2048
	s_mov_b32 s98, 0x1fa00800
	v_lshl_add_u64 v[148:149], v[142:143], 0, s[98:99]
	global_load_dwordx2 v[166:167], v[148:149], off offset:-2048
	s_mov_b32 s98, 0x1ba01000
	v_lshl_add_u64 v[146:147], v[140:141], 0, s[98:99]
	global_load_dwordx2 v[168:169], v[146:147], off
	s_mov_b32 s98, 0x23a02800
	v_lshl_add_u64 v[144:145], v[140:141], 0, s[98:99]
	global_load_dwordx2 v[170:171], v[144:145], off offset:-2048
	global_load_dwordx2 v[172:173], v[144:145], off offset:2048
	s_mov_b32 s98, 0x1fa00800
	v_lshl_add_u64 v[148:149], v[142:143], 0, s[98:99]
	global_load_dwordx2 v[174:175], v[148:149], off offset:2048
	s_mov_b32 s98, 0x1ba03000
	v_lshl_add_u64 v[146:147], v[140:141], 0, s[98:99]
	global_load_dwordx2 v[176:177], v[146:147], off
	s_mov_b32 s98, 0x23a04800
	v_lshl_add_u64 v[144:145], v[140:141], 0, s[98:99]
	global_load_dwordx2 v[178:179], v[144:145], off offset:-2048
	global_load_dwordx2 v[182:183], v[144:145], off offset:2048
	s_mov_b32 s98, 0x1fa02800
	v_lshl_add_u64 v[148:149], v[142:143], 0, s[98:99]
	global_load_dwordx2 v[184:185], v[148:149], off offset:-2048
	s_mov_b32 s98, 0x1ba05000
	v_lshl_add_u64 v[146:147], v[140:141], 0, s[98:99]
	global_load_dwordx2 v[186:187], v[146:147], off
	s_mov_b32 s98, 0x23a06800
	v_lshl_add_u64 v[144:145], v[140:141], 0, s[98:99]
	global_load_dwordx2 v[190:191], v[144:145], off offset:-2048
	global_load_dwordx2 v[194:195], v[144:145], off offset:2048
	s_mov_b32 s98, 0x1fa02800
	v_lshl_add_u64 v[148:149], v[142:143], 0, s[98:99]
	global_load_dwordx2 v[196:197], v[148:149], off offset:2048
	s_mov_b32 s98, 0x1ba07000
	v_lshl_add_u64 v[146:147], v[140:141], 0, s[98:99]
	global_load_dwordx2 v[198:199], v[146:147], off
	s_branch .Lsb_join
.Lsb_rot5:
	s_mov_b32 s98, 0x23a0a800
	v_lshl_add_u64 v[144:145], v[140:141], 0, s[98:99]
	global_load_dwordx2 v[208:209], v[144:145], off offset:-2048
	global_load_dwordx2 v[210:211], v[144:145], off offset:2048
	s_mov_b32 s98, 0x1fa04800
	v_lshl_add_u64 v[148:149], v[142:143], 0, s[98:99]
	global_load_dwordx2 v[212:213], v[148:149], off offset:2048
	s_mov_b32 s98, 0x1ba0b000
	v_lshl_add_u64 v[146:147], v[140:141], 0, s[98:99]
	global_load_dwordx2 v[214:215], v[146:147], off
	s_mov_b32 s98, 0x23a0c800
	v_lshl_add_u64 v[144:145], v[140:141], 0, s[98:99]
	global_load_dwordx2 v[216:217], v[144:145], off offset:-2048
	global_load_dwordx2 v[218:219], v[144:145], off offset:2048
	s_mov_b32 s98, 0x1fa06800
	v_lshl_add_u64 v[148:149], v[142:143], 0, s[98:99]
	global_load_dwordx2 v[222:223], v[148:149], off offset:-2048
	s_mov_b32 s98, 0x1ba0d000
	v_lshl_add_u64 v[146:147], v[140:141], 0, s[98:99]
	global_load_dwordx2 v[224:225], v[146:147], off
	s_mov_b32 s98, 0x23a0e800
	v_lshl_add_u64 v[144:145], v[140:141], 0, s[98:99]
	global_load_dwordx2 v[226:227], v[144:145], off offset:-2048
	global_load_dwordx2 v[232:233], v[144:145], off offset:2048
	s_mov_b32 s98, 0x1fa06800
	v_lshl_add_u64 v[148:149], v[142:143], 0, s[98:99]
	global_load_dwordx2 v[234:235], v[148:149], off offset:2048
	s_mov_b32 s98, 0x1ba0f000
	v_lshl_add_u64 v[146:147], v[140:141], 0, s[98:99]
	global_load_dwordx2 v[238:239], v[146:147], off
	s_mov_b32 s98, 0x23a00800
	v_lshl_add_u64 v[144:145], v[140:141], 0, s[98:99]
	global_load_dwordx2 v[162:163], v[144:145], off offset:-2048
	global_load_dwordx2 v[164:165], v[144:145], off offset:2048
	s_mov_b32 s98, 0x1fa00800
	v_lshl_add_u64 v[148:149], v[142:143], 0, s[98:99]
	global_load_dwordx2 v[166:167], v[148:149], off offset:-2048
	s_mov_b32 s98, 0x1ba01000
	v_lshl_add_u64 v[146:147], v[140:141], 0, s[98:99]
	global_load_dwordx2 v[168:169], v[146:147], off
	s_mov_b32 s98, 0x23a02800
	v_lshl_add_u64 v[144:145], v[140:141], 0, s[98:99]
	global_load_dwordx2 v[170:171], v[144:145], off offset:-2048
	global_load_dwordx2 v[172:173], v[144:145], off offset:2048
	s_mov_b32 s98, 0x1fa00800
	v_lshl_add_u64 v[148:149], v[142:143], 0, s[98:99]
	global_load_dwordx2 v[174:175], v[148:149], off offset:2048
	s_mov_b32 s98, 0x1ba03000
	v_lshl_add_u64 v[146:147], v[140:141], 0, s[98:99]
	global_load_dwordx2 v[176:177], v[146:147], off
	s_mov_b32 s98, 0x23a04800
	v_lshl_add_u64 v[144:145], v[140:141], 0, s[98:99]
	global_load_dwordx2 v[178:179], v[144:145], off offset:-2048
	global_load_dwordx2 v[182:183], v[144:145], off offset:2048
	s_mov_b32 s98, 0x1fa02800
	v_lshl_add_u64 v[148:149], v[142:143], 0, s[98:99]
	global_load_dwordx2 v[184:185], v[148:149], off offset:-2048
	s_mov_b32 s98, 0x1ba05000
	v_lshl_add_u64 v[146:147], v[140:141], 0, s[98:99]
	global_load_dwordx2 v[186:187], v[146:147], off
	s_mov_b32 s98, 0x23a06800
	v_lshl_add_u64 v[144:145], v[140:141], 0, s[98:99]
	global_load_dwordx2 v[190:191], v[144:145], off offset:-2048
	global_load_dwordx2 v[194:195], v[144:145], off offset:2048
	s_mov_b32 s98, 0x1fa02800
	v_lshl_add_u64 v[148:149], v[142:143], 0, s[98:99]
	global_load_dwordx2 v[196:197], v[148:149], off offset:2048
	s_mov_b32 s98, 0x1ba07000
	v_lshl_add_u64 v[146:147], v[140:141], 0, s[98:99]
	global_load_dwordx2 v[198:199], v[146:147], off
	s_mov_b32 s98, 0x23a08800
	v_lshl_add_u64 v[144:145], v[140:141], 0, s[98:99]
	global_load_dwordx2 v[200:201], v[144:145], off offset:-2048
	global_load_dwordx2 v[202:203], v[144:145], off offset:2048
	s_mov_b32 s98, 0x1fa04800
	v_lshl_add_u64 v[148:149], v[142:143], 0, s[98:99]
	global_load_dwordx2 v[204:205], v[148:149], off offset:-2048
	s_mov_b32 s98, 0x1ba09000
	v_lshl_add_u64 v[146:147], v[140:141], 0, s[98:99]
	global_load_dwordx2 v[206:207], v[146:147], off
	s_branch .Lsb_join
.Lsb_rot6:
	s_mov_b32 s98, 0x23a0c800
	v_lshl_add_u64 v[144:145], v[140:141], 0, s[98:99]
	global_load_dwordx2 v[216:217], v[144:145], off offset:-2048
	global_load_dwordx2 v[218:219], v[144:145], off offset:2048
	s_mov_b32 s98, 0x1fa06800
	v_lshl_add_u64 v[148:149], v[142:143], 0, s[98:99]
	global_load_dwordx2 v[222:223], v[148:149], off offset:-2048
	s_mov_b32 s98, 0x1ba0d000
	v_lshl_add_u64 v[146:147], v[140:141], 0, s[98:99]
	global_load_dwordx2 v[224:225], v[146:147], off
	s_mov_b32 s98, 0x23a0e800
	v_lshl_add_u64 v[144:145], v[140:141], 0, s[98:99]
	global_load_dwordx2 v[226:227], v[144:145], off offset:-2048
	global_load_dwordx2 v[232:233], v[144:145], off offset:2048
	s_mov_b32 s98, 0x1fa06800
	v_lshl_add_u64 v[148:149], v[142:143], 0, s[98:99]
	global_load_dwordx2 v[234:235], v[148:149], off offset:2048
	s_mov_b32 s98, 0x1ba0f000
	v_lshl_add_u64 v[146:147], v[140:141], 0, s[98:99]
	global_load_dwordx2 v[238:239], v[146:147], off
	s_mov_b32 s98, 0x23a00800
	v_lshl_add_u64 v[144:145], v[140:141], 0, s[98:99]
	global_load_dwordx2 v[162:163], v[144:145], off offset:-2048
	global_load_dwordx2 v[164:165], v[144:145], off offset:2048
	s_mov_b32 s98, 0x1fa00800
	v_lshl_add_u64 v[148:149], v[142:143], 0, s[98:99]
	global_load_dwordx2 v[166:167], v[148:149], off offset:-2048
	s_mov_b32 s98, 0x1ba01000
	v_lshl_add_u64 v[146:147], v[140:141], 0, s[98:99]
	global_load_dwordx2 v[168:169], v[146:147], off
	s_mov_b32 s98, 0x23a02800
	v_lshl_add_u64 v[144:145], v[140:141], 0, s[98:99]
	global_load_dwordx2 v[170:171], v[144:145], off offset:-2048
	global_load_dwordx2 v[172:173], v[144:145], off offset:2048
	s_mov_b32 s98, 0x1fa00800
	v_lshl_add_u64 v[148:149], v[142:143], 0, s[98:99]
	global_load_dwordx2 v[174:175], v[148:149], off offset:2048
	s_mov_b32 s98, 0x1ba03000
	v_lshl_add_u64 v[146:147], v[140:141], 0, s[98:99]
	global_load_dwordx2 v[176:177], v[146:147], off
	s_mov_b32 s98, 0x23a04800
	v_lshl_add_u64 v[144:145], v[140:141], 0, s[98:99]
	global_load_dwordx2 v[178:179], v[144:145], off offset:-2048
	global_load_dwordx2 v[182:183], v[144:145], off offset:2048
	s_mov_b32 s98, 0x1fa02800
	v_lshl_add_u64 v[148:149], v[142:143], 0, s[98:99]
	global_load_dwordx2 v[184:185], v[148:149], off offset:-2048
	s_mov_b32 s98, 0x1ba05000
	v_lshl_add_u64 v[146:147], v[140:141], 0, s[98:99]
	global_load_dwordx2 v[186:187], v[146:147], off
	s_mov_b32 s98, 0x23a06800
	v_lshl_add_u64 v[144:145], v[140:141], 0, s[98:99]
	global_load_dwordx2 v[190:191], v[144:145], off offset:-2048
	global_load_dwordx2 v[194:195], v[144:145], off offset:2048
	s_mov_b32 s98, 0x1fa02800
	v_lshl_add_u64 v[148:149], v[142:143], 0, s[98:99]
	global_load_dwordx2 v[196:197], v[148:149], off offset:2048
	s_mov_b32 s98, 0x1ba07000
	v_lshl_add_u64 v[146:147], v[140:141], 0, s[98:99]
	global_load_dwordx2 v[198:199], v[146:147], off
	s_mov_b32 s98, 0x23a08800
	v_lshl_add_u64 v[144:145], v[140:141], 0, s[98:99]
	global_load_dwordx2 v[200:201], v[144:145], off offset:-2048
	global_load_dwordx2 v[202:203], v[144:145], off offset:2048
	s_mov_b32 s98, 0x1fa04800
	v_lshl_add_u64 v[148:149], v[142:143], 0, s[98:99]
	global_load_dwordx2 v[204:205], v[148:149], off offset:-2048
	s_mov_b32 s98, 0x1ba09000
	v_lshl_add_u64 v[146:147], v[140:141], 0, s[98:99]
	global_load_dwordx2 v[206:207], v[146:147], off
	s_mov_b32 s98, 0x23a0a800
	v_lshl_add_u64 v[144:145], v[140:141], 0, s[98:99]
	global_load_dwordx2 v[208:209], v[144:145], off offset:-2048
	global_load_dwordx2 v[210:211], v[144:145], off offset:2048
	s_mov_b32 s98, 0x1fa04800
	v_lshl_add_u64 v[148:149], v[142:143], 0, s[98:99]
	global_load_dwordx2 v[212:213], v[148:149], off offset:2048
	s_mov_b32 s98, 0x1ba0b000
	v_lshl_add_u64 v[146:147], v[140:141], 0, s[98:99]
	global_load_dwordx2 v[214:215], v[146:147], off
	s_branch .Lsb_join
.Lsb_join:
	v_add_co_u32_e32 v148, vcc, 0x1fa00000, v142
	v_lshl_add_u64 v[132:133], v[132:133], 0, s[6:7]
	s_nop 0
	v_addc_co_u32_e32 v149, vcc, 0, v143, vcc
	s_mov_b64 s[6:7], 0x10000
	s_add_i32 s0, s0, -8
	v_lshl_add_u64 v[134:135], v[134:135], 0, s[6:7]
	s_cmp_eq_u32 s0, 0
	s_waitcnt vmcnt(0)
	v_lshlrev_b32_e32 v150, 16, v162
	v_and_b32_e32 v151, 0xffff0000, v162
	v_lshlrev_b32_e32 v154, 16, v163
	v_and_b32_e32 v155, 0xffff0000, v163
	v_lshlrev_b32_e32 v144, 16, v164
	v_and_b32_e32 v145, 0xffff0000, v164
	v_add_f32_e32 v146, v68, v150
	v_mul_f32_e32 v146, 0xbfb8aa3b, v146
	v_exp_f32_e32 v146, v146
	v_lshlrev_b32_e32 v156, 16, v165
	v_and_b32_e32 v157, 0xffff0000, v165
	v_add_f32_e32 v144, v64, v144
	v_add_f32_e32 v146, 1.0, v146
	v_rcp_f32_e32 v146, v146
	v_add_f32_e32 v145, v65, v145
	v_mul_f32_e32 v144, 0xbfb8aa3b, v144
	v_mul_f32_e32 v145, 0xbfb8aa3b, v145
	v_mul_f32_e32 v146, v72, v146
	v_exp_f32_e32 v146, v146
	v_exp_f32_e32 v144, v144
	v_exp_f32_e32 v145, v145
	v_and_b32_e32 v153, 0xffff0000, v166
	v_sub_f32_e32 v147, 1.0, v146
	v_add_f32_e32 v150, 1.0, v146
	v_mul_f32_e32 v147, v147, v150
	v_sqrt_f32_e32 v150, v147
	v_add_f32_e32 v147, v69, v151
	v_mul_f32_e32 v147, 0xbfb8aa3b, v147
	v_exp_f32_e32 v147, v147
	v_add_f32_e32 v144, 1.0, v144
	v_add_f32_e32 v145, 1.0, v145
	v_rcp_f32_e32 v144, v144
	v_add_f32_e32 v147, 1.0, v147
	v_rcp_f32_e32 v147, v147
	v_rcp_f32_e32 v145, v145
	v_mul_f32_e32 v147, v73, v147
	v_exp_f32_e32 v147, v147
	s_nop 0
	v_sub_f32_e32 v151, 1.0, v147
	v_add_f32_e32 v152, 1.0, v147
	v_mul_f32_e32 v151, v151, v152
	v_sqrt_f32_e32 v151, v151
	v_lshlrev_b32_e32 v152, 16, v166
	v_pk_mul_f32 v[144:145], v[144:145], v[152:153]
	v_add_f32_e32 v148, v70, v154
	v_pk_mul_f32 v[144:145], v[144:145], v[150:151]
	v_mul_f32_e32 v148, 0xbfb8aa3b, v148
	v_pk_fma_f32 v[138:139], v[138:139], v[146:147], v[144:145]
	v_add_co_u32_e32 v144, vcc, s1, v140
	v_exp_f32_e32 v148, v148
	s_nop 0
	v_addc_co_u32_e32 v145, vcc, 0, v141, vcc
	v_add_f32_e32 v148, 1.0, v148
	v_rcp_f32_e32 v148, v148
	v_add_f32_e32 v150, v66, v156
	v_mul_f32_e32 v150, 0xbfb8aa3b, v150
	v_exp_f32_e32 v150, v150
	v_mul_f32_e32 v148, v74, v148
	v_exp_f32_e32 v152, v148
	s_mov_b32 s1, 0x21a01000
	v_add_f32_e32 v150, 1.0, v150
	v_rcp_f32_e32 v150, v150
	v_sub_f32_e32 v148, 1.0, v152
	v_add_f32_e32 v151, 1.0, v152
	v_mul_f32_e32 v148, v148, v151
	v_sqrt_f32_e32 v154, v148
	v_add_f32_e32 v148, v71, v155
	v_mul_f32_e32 v148, 0xbfb8aa3b, v148
	v_exp_f32_e32 v148, v148
	v_add_f32_e32 v151, v67, v157
	v_mul_f32_e32 v151, 0xbfb8aa3b, v151
	v_exp_f32_e32 v151, v151
	v_add_f32_e32 v148, 1.0, v148
	v_rcp_f32_e32 v148, v148
	v_add_f32_e32 v151, 1.0, v151
	v_rcp_f32_e32 v151, v151
	v_mul_f32_e32 v148, v75, v148
	v_exp_f32_e32 v153, v148
	v_lshlrev_b32_e32 v146, 16, v168
	v_sub_f32_e32 v148, 1.0, v153
	v_add_f32_e32 v155, 1.0, v153
	v_mul_f32_e32 v148, v148, v155
	v_sqrt_f32_e32 v155, v148
	v_lshlrev_b32_e32 v148, 16, v167
	v_and_b32_e32 v149, 0xffff0000, v167
	v_pk_mul_f32 v[148:149], v[150:151], v[148:149]
	v_and_b32_e32 v147, 0xffff0000, v168
	v_pk_mul_f32 v[148:149], v[148:149], v[154:155]
	v_pk_mul_f32 v[146:147], v[138:139], v[146:147]
	v_pk_fma_f32 v[136:137], v[136:137], v[152:153], v[148:149]
	v_cvt_pk_bf16_f32 v144, v146, v147
	v_lshlrev_b32_e32 v146, 16, v169
	v_and_b32_e32 v147, 0xffff0000, v169
	v_pk_mul_f32 v[146:147], v[136:137], v[146:147]
	s_nop 0
	v_cvt_pk_bf16_f32 v145, v146, v147
	v_add_co_u32_e32 v146, vcc, s1, v142
	s_mov_b32 s1, 0x23a03000
	s_nop 0
	v_addc_co_u32_e32 v147, vcc, 0, v143, vcc
	global_store_dwordx2 v[146:147], v[144:145], off offset:-4096
	v_add_co_u32_e32 v144, vcc, s1, v140
	s_mov_b32 s1, 0x1fa02000
	s_nop 0
	v_addc_co_u32_e32 v145, vcc, 0, v141, vcc
	s_nop 0
	v_add_co_u32_e32 v150, vcc, s1, v142
	s_mov_b32 s1, 0x1ba03000
	s_nop 0
	v_addc_co_u32_e32 v151, vcc, 0, v143, vcc
	v_lshlrev_b32_e32 v154, 16, v170
	v_and_b32_e32 v155, 0xffff0000, v170
	v_lshlrev_b32_e32 v158, 16, v171
	v_and_b32_e32 v159, 0xffff0000, v171
	v_lshlrev_b32_e32 v148, 16, v172
	v_and_b32_e32 v149, 0xffff0000, v172
	v_add_f32_e32 v144, v68, v154
	v_mul_f32_e32 v144, 0xbfb8aa3b, v144
	v_exp_f32_e32 v144, v144
	v_lshlrev_b32_e32 v160, 16, v173
	v_and_b32_e32 v161, 0xffff0000, v173
	v_and_b32_e32 v157, 0xffff0000, v174
	v_add_f32_e32 v144, 1.0, v144
	v_rcp_f32_e32 v145, v144
	v_add_f32_e32 v144, v64, v148
	v_mul_f32_e32 v144, 0xbfb8aa3b, v144
	v_exp_f32_e32 v144, v144
	v_mul_f32_e32 v145, v72, v145
	v_exp_f32_e32 v148, v145
	v_add_f32_e32 v144, 1.0, v144
	v_rcp_f32_e32 v144, v144
	v_sub_f32_e32 v145, 1.0, v148
	v_add_f32_e32 v154, 1.0, v148
	v_mul_f32_e32 v145, v145, v154
	v_sqrt_f32_e32 v154, v145
	v_add_f32_e32 v145, v69, v155
	v_mul_f32_e32 v145, 0xbfb8aa3b, v145
	v_exp_f32_e32 v145, v145
	s_nop 0
	v_add_f32_e32 v145, 1.0, v145
	v_rcp_f32_e32 v155, v145
	v_add_f32_e32 v145, v65, v149
	v_mul_f32_e32 v145, 0xbfb8aa3b, v145
	v_exp_f32_e32 v145, v145
	v_mul_f32_e32 v149, v73, v155
	v_exp_f32_e32 v149, v149
	v_add_f32_e32 v145, 1.0, v145
	v_rcp_f32_e32 v145, v145
	v_sub_f32_e32 v155, 1.0, v149
	v_add_f32_e32 v156, 1.0, v149
	v_mul_f32_e32 v155, v155, v156
	v_sqrt_f32_e32 v155, v155
	v_lshlrev_b32_e32 v156, 16, v174
	v_pk_mul_f32 v[144:145], v[144:145], v[156:157]
	v_add_f32_e32 v152, v70, v158
	v_pk_mul_f32 v[144:145], v[144:145], v[154:155]
	v_mul_f32_e32 v152, 0xbfb8aa3b, v152
	v_pk_fma_f32 v[138:139], v[138:139], v[148:149], v[144:145]
	v_add_co_u32_e32 v144, vcc, s1, v140
	v_exp_f32_e32 v152, v152
	s_nop 0
	v_addc_co_u32_e32 v145, vcc, 0, v141, vcc
	v_add_f32_e32 v152, 1.0, v152
	v_rcp_f32_e32 v152, v152
	v_add_f32_e32 v154, v66, v160
	v_mul_f32_e32 v154, 0xbfb8aa3b, v154
	v_exp_f32_e32 v154, v154
	v_mul_f32_e32 v152, v74, v152
	v_exp_f32_e32 v156, v152
	s_mov_b32 s1, 0x23a05000
	v_add_f32_e32 v154, 1.0, v154
	v_rcp_f32_e32 v154, v154
	v_sub_f32_e32 v152, 1.0, v156
	v_add_f32_e32 v155, 1.0, v156
	v_mul_f32_e32 v152, v152, v155
	v_sqrt_f32_e32 v158, v152
	v_add_f32_e32 v152, v71, v159
	v_mul_f32_e32 v152, 0xbfb8aa3b, v152
	v_exp_f32_e32 v152, v152
	v_add_f32_e32 v155, v67, v161
	v_mul_f32_e32 v155, 0xbfb8aa3b, v155
	v_exp_f32_e32 v155, v155
	v_add_f32_e32 v152, 1.0, v152
	v_rcp_f32_e32 v152, v152
	v_add_f32_e32 v155, 1.0, v155
	v_rcp_f32_e32 v155, v155
	v_mul_f32_e32 v152, v75, v152
	v_exp_f32_e32 v157, v152
	v_lshlrev_b32_e32 v148, 16, v176
	v_sub_f32_e32 v152, 1.0, v157
	v_add_f32_e32 v159, 1.0, v157
	v_mul_f32_e32 v152, v152, v159
	v_sqrt_f32_e32 v159, v152
	v_lshlrev_b32_e32 v152, 16, v175
	v_and_b32_e32 v153, 0xffff0000, v175
	v_pk_mul_f32 v[152:153], v[154:155], v[152:153]
	v_and_b32_e32 v149, 0xffff0000, v176
	v_pk_mul_f32 v[152:153], v[152:153], v[158:159]
	v_pk_mul_f32 v[148:149], v[138:139], v[148:149]
	v_pk_fma_f32 v[136:137], v[136:137], v[156:157], v[152:153]
	v_cvt_pk_bf16_f32 v144, v148, v149
	v_lshlrev_b32_e32 v148, 16, v177
	v_and_b32_e32 v149, 0xffff0000, v177
	v_pk_mul_f32 v[148:149], v[136:137], v[148:149]
	s_nop 0
	v_cvt_pk_bf16_f32 v145, v148, v149
	global_store_dwordx2 v[146:147], v[144:145], off
	v_add_co_u32_e32 v144, vcc, s1, v140
	s_mov_b32 s1, 0x1ba05000
	s_nop 0
	v_addc_co_u32_e32 v145, vcc, 0, v141, vcc
	s_nop 0
	s_nop 0
	v_lshlrev_b32_e32 v150, 16, v178
	v_and_b32_e32 v151, 0xffff0000, v178
	v_lshlrev_b32_e32 v154, 16, v179
	v_and_b32_e32 v155, 0xffff0000, v179
	v_lshlrev_b32_e32 v146, 16, v182
	v_and_b32_e32 v147, 0xffff0000, v182
	v_add_f32_e32 v144, v68, v150
	v_mul_f32_e32 v144, 0xbfb8aa3b, v144
	v_exp_f32_e32 v144, v144
	v_lshlrev_b32_e32 v156, 16, v183
	v_and_b32_e32 v157, 0xffff0000, v183
	v_and_b32_e32 v153, 0xffff0000, v184
	v_add_f32_e32 v144, 1.0, v144
	v_rcp_f32_e32 v145, v144
	v_add_f32_e32 v144, v64, v146
	v_mul_f32_e32 v144, 0xbfb8aa3b, v144
	v_exp_f32_e32 v144, v144
	v_mul_f32_e32 v145, v72, v145
	v_exp_f32_e32 v146, v145
	v_add_f32_e32 v144, 1.0, v144
	v_rcp_f32_e32 v144, v144
	v_sub_f32_e32 v145, 1.0, v146
	v_add_f32_e32 v150, 1.0, v146
	v_mul_f32_e32 v145, v145, v150
	v_sqrt_f32_e32 v150, v145
	v_add_f32_e32 v145, v69, v151
	v_mul_f32_e32 v145, 0xbfb8aa3b, v145
	v_exp_f32_e32 v145, v145
	s_nop 0
	v_add_f32_e32 v145, 1.0, v145
	v_rcp_f32_e32 v151, v145
	v_add_f32_e32 v145, v65, v147
	v_mul_f32_e32 v145, 0xbfb8aa3b, v145
	v_exp_f32_e32 v145, v145
	v_mul_f32_e32 v147, v73, v151
	v_exp_f32_e32 v147, v147
	v_add_f32_e32 v145, 1.0, v145
	v_rcp_f32_e32 v145, v145
	v_sub_f32_e32 v151, 1.0, v147
	v_add_f32_e32 v152, 1.0, v147
	v_mul_f32_e32 v151, v151, v152
	v_sqrt_f32_e32 v151, v151
	v_lshlrev_b32_e32 v152, 16, v184
	v_pk_mul_f32 v[144:145], v[144:145], v[152:153]
	v_add_f32_e32 v148, v70, v154
	v_pk_mul_f32 v[144:145], v[144:145], v[150:151]
	v_mul_f32_e32 v148, 0xbfb8aa3b, v148
	v_pk_fma_f32 v[138:139], v[138:139], v[146:147], v[144:145]
	v_add_co_u32_e32 v144, vcc, s1, v140
	v_exp_f32_e32 v148, v148
	s_nop 0
	v_addc_co_u32_e32 v145, vcc, 0, v141, vcc
	v_add_f32_e32 v148, 1.0, v148
	v_rcp_f32_e32 v148, v148
	v_add_f32_e32 v150, v66, v156
	v_mul_f32_e32 v150, 0xbfb8aa3b, v150
	v_exp_f32_e32 v150, v150
	v_mul_f32_e32 v148, v74, v148
	v_exp_f32_e32 v152, v148
	s_mov_b32 s1, 0x21a03000
	v_add_f32_e32 v150, 1.0, v150
	v_rcp_f32_e32 v150, v150
	v_sub_f32_e32 v148, 1.0, v152
	v_add_f32_e32 v151, 1.0, v152
	v_mul_f32_e32 v148, v148, v151
	v_sqrt_f32_e32 v154, v148
	v_add_f32_e32 v148, v71, v155
	v_mul_f32_e32 v148, 0xbfb8aa3b, v148
	v_exp_f32_e32 v148, v148
	v_add_f32_e32 v151, v67, v157
	v_mul_f32_e32 v151, 0xbfb8aa3b, v151
	v_exp_f32_e32 v151, v151
	v_add_f32_e32 v148, 1.0, v148
	v_rcp_f32_e32 v148, v148
	v_add_f32_e32 v151, 1.0, v151
	v_rcp_f32_e32 v151, v151
	v_mul_f32_e32 v148, v75, v148
	v_exp_f32_e32 v153, v148
	v_lshlrev_b32_e32 v146, 16, v186
	v_sub_f32_e32 v148, 1.0, v153
	v_add_f32_e32 v155, 1.0, v153
	v_mul_f32_e32 v148, v148, v155
	v_sqrt_f32_e32 v155, v148
	v_lshlrev_b32_e32 v148, 16, v185
	v_and_b32_e32 v149, 0xffff0000, v185
	v_pk_mul_f32 v[148:149], v[150:151], v[148:149]
	v_and_b32_e32 v147, 0xffff0000, v186
	v_pk_mul_f32 v[148:149], v[148:149], v[154:155]
	v_pk_mul_f32 v[146:147], v[138:139], v[146:147]
	v_pk_fma_f32 v[136:137], v[136:137], v[152:153], v[148:149]
	v_cvt_pk_bf16_f32 v144, v146, v147
	v_lshlrev_b32_e32 v146, 16, v187
	v_and_b32_e32 v147, 0xffff0000, v187
	v_pk_mul_f32 v[146:147], v[136:137], v[146:147]
	s_nop 0
	v_cvt_pk_bf16_f32 v145, v146, v147
	v_add_co_u32_e32 v146, vcc, s1, v142
	s_mov_b32 s1, 0x23a07000
	s_nop 0
	v_addc_co_u32_e32 v147, vcc, 0, v143, vcc
	global_store_dwordx2 v[146:147], v[144:145], off offset:-4096
	v_add_co_u32_e32 v144, vcc, s1, v140
	s_mov_b32 s1, 0x1fa04000
	s_nop 0
	v_addc_co_u32_e32 v145, vcc, 0, v141, vcc
	s_nop 0
	v_add_co_u32_e32 v150, vcc, s1, v142
	s_mov_b32 s1, 0x1ba07000
	s_nop 0
	v_addc_co_u32_e32 v151, vcc, 0, v143, vcc
	v_lshlrev_b32_e32 v154, 16, v190
	v_and_b32_e32 v155, 0xffff0000, v190
	v_lshlrev_b32_e32 v158, 16, v191
	v_and_b32_e32 v159, 0xffff0000, v191
	v_lshlrev_b32_e32 v148, 16, v194
	v_and_b32_e32 v149, 0xffff0000, v194
	v_add_f32_e32 v144, v68, v154
	v_mul_f32_e32 v144, 0xbfb8aa3b, v144
	v_exp_f32_e32 v144, v144
	v_lshlrev_b32_e32 v160, 16, v195
	v_and_b32_e32 v161, 0xffff0000, v195
	v_and_b32_e32 v157, 0xffff0000, v196
	v_add_f32_e32 v144, 1.0, v144
	v_rcp_f32_e32 v145, v144
	v_add_f32_e32 v144, v64, v148
	v_mul_f32_e32 v144, 0xbfb8aa3b, v144
	v_exp_f32_e32 v144, v144
	v_mul_f32_e32 v145, v72, v145
	v_exp_f32_e32 v148, v145
	v_add_f32_e32 v144, 1.0, v144
	v_rcp_f32_e32 v144, v144
	v_sub_f32_e32 v145, 1.0, v148
	v_add_f32_e32 v154, 1.0, v148
	v_mul_f32_e32 v145, v145, v154
	v_sqrt_f32_e32 v154, v145
	v_add_f32_e32 v145, v69, v155
	v_mul_f32_e32 v145, 0xbfb8aa3b, v145
	v_exp_f32_e32 v145, v145
	s_nop 0
	v_add_f32_e32 v145, 1.0, v145
	v_rcp_f32_e32 v155, v145
	v_add_f32_e32 v145, v65, v149
	v_mul_f32_e32 v145, 0xbfb8aa3b, v145
	v_exp_f32_e32 v145, v145
	v_mul_f32_e32 v149, v73, v155
	v_exp_f32_e32 v149, v149
	v_add_f32_e32 v145, 1.0, v145
	v_rcp_f32_e32 v145, v145
	v_sub_f32_e32 v155, 1.0, v149
	v_add_f32_e32 v156, 1.0, v149
	v_mul_f32_e32 v155, v155, v156
	v_sqrt_f32_e32 v155, v155
	v_lshlrev_b32_e32 v156, 16, v196
	v_pk_mul_f32 v[144:145], v[144:145], v[156:157]
	v_add_f32_e32 v152, v70, v158
	v_pk_mul_f32 v[144:145], v[144:145], v[154:155]
	v_mul_f32_e32 v152, 0xbfb8aa3b, v152
	v_pk_fma_f32 v[138:139], v[138:139], v[148:149], v[144:145]
	v_add_co_u32_e32 v144, vcc, s1, v140
	v_exp_f32_e32 v152, v152
	s_nop 0
	v_addc_co_u32_e32 v145, vcc, 0, v141, vcc
	v_add_f32_e32 v152, 1.0, v152
	v_rcp_f32_e32 v152, v152
	v_add_f32_e32 v154, v66, v160
	v_mul_f32_e32 v154, 0xbfb8aa3b, v154
	v_exp_f32_e32 v154, v154
	v_mul_f32_e32 v152, v74, v152
	v_exp_f32_e32 v156, v152
	s_mov_b32 s1, 0x23a09000
	v_add_f32_e32 v154, 1.0, v154
	v_rcp_f32_e32 v154, v154
	v_sub_f32_e32 v152, 1.0, v156
	v_add_f32_e32 v155, 1.0, v156
	v_mul_f32_e32 v152, v152, v155
	v_sqrt_f32_e32 v158, v152
	v_add_f32_e32 v152, v71, v159
	v_mul_f32_e32 v152, 0xbfb8aa3b, v152
	v_exp_f32_e32 v152, v152
	v_add_f32_e32 v155, v67, v161
	v_mul_f32_e32 v155, 0xbfb8aa3b, v155
	v_exp_f32_e32 v155, v155
	v_add_f32_e32 v152, 1.0, v152
	v_rcp_f32_e32 v152, v152
	v_add_f32_e32 v155, 1.0, v155
	v_rcp_f32_e32 v155, v155
	v_mul_f32_e32 v152, v75, v152
	v_exp_f32_e32 v157, v152
	v_lshlrev_b32_e32 v148, 16, v198
	v_sub_f32_e32 v152, 1.0, v157
	v_add_f32_e32 v159, 1.0, v157
	v_mul_f32_e32 v152, v152, v159
	v_sqrt_f32_e32 v159, v152
	v_lshlrev_b32_e32 v152, 16, v197
	v_and_b32_e32 v153, 0xffff0000, v197
	v_pk_mul_f32 v[152:153], v[154:155], v[152:153]
	v_and_b32_e32 v149, 0xffff0000, v198
	v_pk_mul_f32 v[152:153], v[152:153], v[158:159]
	v_pk_mul_f32 v[148:149], v[138:139], v[148:149]
	v_pk_fma_f32 v[136:137], v[136:137], v[156:157], v[152:153]
	v_cvt_pk_bf16_f32 v144, v148, v149
	v_lshlrev_b32_e32 v148, 16, v199
	v_and_b32_e32 v149, 0xffff0000, v199
	v_pk_mul_f32 v[148:149], v[136:137], v[148:149]
	s_nop 0
	v_cvt_pk_bf16_f32 v145, v148, v149
	global_store_dwordx2 v[146:147], v[144:145], off
	v_add_co_u32_e32 v144, vcc, s1, v140
	s_mov_b32 s1, 0x1ba09000
	s_nop 0
	v_addc_co_u32_e32 v145, vcc, 0, v141, vcc
	s_nop 0
	s_nop 0
	v_lshlrev_b32_e32 v150, 16, v200
	v_and_b32_e32 v151, 0xffff0000, v200
	v_lshlrev_b32_e32 v154, 16, v201
	v_and_b32_e32 v155, 0xffff0000, v201
	v_lshlrev_b32_e32 v146, 16, v202
	v_and_b32_e32 v147, 0xffff0000, v202
	v_add_f32_e32 v144, v68, v150
	v_mul_f32_e32 v144, 0xbfb8aa3b, v144
	v_exp_f32_e32 v144, v144
	v_lshlrev_b32_e32 v156, 16, v203
	v_and_b32_e32 v157, 0xffff0000, v203
	v_and_b32_e32 v153, 0xffff0000, v204
	v_add_f32_e32 v144, 1.0, v144
	v_rcp_f32_e32 v145, v144
	v_add_f32_e32 v144, v64, v146
	v_mul_f32_e32 v144, 0xbfb8aa3b, v144
	v_exp_f32_e32 v144, v144
	v_mul_f32_e32 v145, v72, v145
	v_exp_f32_e32 v146, v145
	v_add_f32_e32 v144, 1.0, v144
	v_rcp_f32_e32 v144, v144
	v_sub_f32_e32 v145, 1.0, v146
	v_add_f32_e32 v150, 1.0, v146
	v_mul_f32_e32 v145, v145, v150
	v_sqrt_f32_e32 v150, v145
	v_add_f32_e32 v145, v69, v151
	v_mul_f32_e32 v145, 0xbfb8aa3b, v145
	v_exp_f32_e32 v145, v145
	s_nop 0
	v_add_f32_e32 v145, 1.0, v145
	v_rcp_f32_e32 v151, v145
	v_add_f32_e32 v145, v65, v147
	v_mul_f32_e32 v145, 0xbfb8aa3b, v145
	v_exp_f32_e32 v145, v145
	v_mul_f32_e32 v147, v73, v151
	v_exp_f32_e32 v147, v147
	v_add_f32_e32 v145, 1.0, v145
	v_rcp_f32_e32 v145, v145
	v_sub_f32_e32 v151, 1.0, v147
	v_add_f32_e32 v152, 1.0, v147
	v_mul_f32_e32 v151, v151, v152
	v_sqrt_f32_e32 v151, v151
	v_lshlrev_b32_e32 v152, 16, v204
	v_pk_mul_f32 v[144:145], v[144:145], v[152:153]
	v_add_f32_e32 v148, v70, v154
	v_pk_mul_f32 v[144:145], v[144:145], v[150:151]
	v_mul_f32_e32 v148, 0xbfb8aa3b, v148
	v_pk_fma_f32 v[138:139], v[138:139], v[146:147], v[144:145]
	v_add_co_u32_e32 v144, vcc, s1, v140
	v_exp_f32_e32 v148, v148
	s_nop 0
	v_addc_co_u32_e32 v145, vcc, 0, v141, vcc
	v_add_f32_e32 v148, 1.0, v148
	v_rcp_f32_e32 v148, v148
	v_add_f32_e32 v150, v66, v156
	v_mul_f32_e32 v150, 0xbfb8aa3b, v150
	v_exp_f32_e32 v150, v150
	v_mul_f32_e32 v148, v74, v148
	v_exp_f32_e32 v152, v148
	s_mov_b32 s1, 0x21a05000
	v_add_f32_e32 v150, 1.0, v150
	v_rcp_f32_e32 v150, v150
	v_sub_f32_e32 v148, 1.0, v152
	v_add_f32_e32 v151, 1.0, v152
	v_mul_f32_e32 v148, v148, v151
	v_sqrt_f32_e32 v154, v148
	v_add_f32_e32 v148, v71, v155
	v_mul_f32_e32 v148, 0xbfb8aa3b, v148
	v_exp_f32_e32 v148, v148
	v_add_f32_e32 v151, v67, v157
	v_mul_f32_e32 v151, 0xbfb8aa3b, v151
	v_exp_f32_e32 v151, v151
	v_add_f32_e32 v148, 1.0, v148
	v_rcp_f32_e32 v148, v148
	v_add_f32_e32 v151, 1.0, v151
	v_rcp_f32_e32 v151, v151
	v_mul_f32_e32 v148, v75, v148
	v_exp_f32_e32 v153, v148
	v_lshlrev_b32_e32 v146, 16, v206
	v_sub_f32_e32 v148, 1.0, v153
	v_add_f32_e32 v155, 1.0, v153
	v_mul_f32_e32 v148, v148, v155
	v_sqrt_f32_e32 v155, v148
	v_lshlrev_b32_e32 v148, 16, v205
	v_and_b32_e32 v149, 0xffff0000, v205
	v_pk_mul_f32 v[148:149], v[150:151], v[148:149]
	v_and_b32_e32 v147, 0xffff0000, v206
	v_pk_mul_f32 v[148:149], v[148:149], v[154:155]
	v_pk_mul_f32 v[146:147], v[138:139], v[146:147]
	v_pk_fma_f32 v[136:137], v[136:137], v[152:153], v[148:149]
	v_cvt_pk_bf16_f32 v144, v146, v147
	v_lshlrev_b32_e32 v146, 16, v207
	v_and_b32_e32 v147, 0xffff0000, v207
	v_pk_mul_f32 v[146:147], v[136:137], v[146:147]
	s_nop 0
	v_cvt_pk_bf16_f32 v145, v146, v147
	v_add_co_u32_e32 v146, vcc, s1, v142
	s_mov_b32 s1, 0x23a0b000
	s_nop 0
	v_addc_co_u32_e32 v147, vcc, 0, v143, vcc
	global_store_dwordx2 v[146:147], v[144:145], off offset:-4096
	v_add_co_u32_e32 v144, vcc, s1, v140
	s_mov_b32 s1, 0x1fa06000
	s_nop 0
	v_addc_co_u32_e32 v145, vcc, 0, v141, vcc
	s_nop 0
	v_add_co_u32_e32 v150, vcc, s1, v142
	s_mov_b32 s1, 0x1ba0b000
	s_nop 0
	v_addc_co_u32_e32 v151, vcc, 0, v143, vcc
	v_lshlrev_b32_e32 v154, 16, v208
	v_and_b32_e32 v155, 0xffff0000, v208
	v_lshlrev_b32_e32 v158, 16, v209
	v_and_b32_e32 v159, 0xffff0000, v209
	v_lshlrev_b32_e32 v148, 16, v210
	v_and_b32_e32 v149, 0xffff0000, v210
	v_add_f32_e32 v144, v68, v154
	v_mul_f32_e32 v144, 0xbfb8aa3b, v144
	v_exp_f32_e32 v144, v144
	v_lshlrev_b32_e32 v160, 16, v211
	v_and_b32_e32 v161, 0xffff0000, v211
	v_and_b32_e32 v157, 0xffff0000, v212
	v_add_f32_e32 v144, 1.0, v144
	v_rcp_f32_e32 v145, v144
	v_add_f32_e32 v144, v64, v148
	v_mul_f32_e32 v144, 0xbfb8aa3b, v144
	v_exp_f32_e32 v144, v144
	v_mul_f32_e32 v145, v72, v145
	v_exp_f32_e32 v148, v145
	v_add_f32_e32 v144, 1.0, v144
	v_rcp_f32_e32 v144, v144
	v_sub_f32_e32 v145, 1.0, v148
	v_add_f32_e32 v154, 1.0, v148
	v_mul_f32_e32 v145, v145, v154
	v_sqrt_f32_e32 v154, v145
	v_add_f32_e32 v145, v69, v155
	v_mul_f32_e32 v145, 0xbfb8aa3b, v145
	v_exp_f32_e32 v145, v145
	s_nop 0
	v_add_f32_e32 v145, 1.0, v145
	v_rcp_f32_e32 v155, v145
	v_add_f32_e32 v145, v65, v149
	v_mul_f32_e32 v145, 0xbfb8aa3b, v145
	v_exp_f32_e32 v145, v145
	v_mul_f32_e32 v149, v73, v155
	v_exp_f32_e32 v149, v149
	v_add_f32_e32 v145, 1.0, v145
	v_rcp_f32_e32 v145, v145
	v_sub_f32_e32 v155, 1.0, v149
	v_add_f32_e32 v156, 1.0, v149
	v_mul_f32_e32 v155, v155, v156
	v_sqrt_f32_e32 v155, v155
	v_lshlrev_b32_e32 v156, 16, v212
	v_pk_mul_f32 v[144:145], v[144:145], v[156:157]
	v_add_f32_e32 v152, v70, v158
	v_pk_mul_f32 v[144:145], v[144:145], v[154:155]
	v_mul_f32_e32 v152, 0xbfb8aa3b, v152
	v_pk_fma_f32 v[138:139], v[138:139], v[148:149], v[144:145]
	v_add_co_u32_e32 v144, vcc, s1, v140
	v_exp_f32_e32 v152, v152
	s_nop 0
	v_addc_co_u32_e32 v145, vcc, 0, v141, vcc
	v_add_f32_e32 v152, 1.0, v152
	v_rcp_f32_e32 v152, v152
	v_add_f32_e32 v154, v66, v160
	v_mul_f32_e32 v154, 0xbfb8aa3b, v154
	v_exp_f32_e32 v154, v154
	v_mul_f32_e32 v152, v74, v152
	v_exp_f32_e32 v156, v152
	s_mov_b32 s1, 0x23a0d000
	v_add_f32_e32 v154, 1.0, v154
	v_rcp_f32_e32 v154, v154
	v_sub_f32_e32 v152, 1.0, v156
	v_add_f32_e32 v155, 1.0, v156
	v_mul_f32_e32 v152, v152, v155
	v_sqrt_f32_e32 v158, v152
	v_add_f32_e32 v152, v71, v159
	v_mul_f32_e32 v152, 0xbfb8aa3b, v152
	v_exp_f32_e32 v152, v152
	v_add_f32_e32 v155, v67, v161
	v_mul_f32_e32 v155, 0xbfb8aa3b, v155
	v_exp_f32_e32 v155, v155
	v_add_f32_e32 v152, 1.0, v152
	v_rcp_f32_e32 v152, v152
	v_add_f32_e32 v155, 1.0, v155
	v_rcp_f32_e32 v155, v155
	v_mul_f32_e32 v152, v75, v152
	v_exp_f32_e32 v157, v152
	v_lshlrev_b32_e32 v148, 16, v214
	v_sub_f32_e32 v152, 1.0, v157
	v_add_f32_e32 v159, 1.0, v157
	v_mul_f32_e32 v152, v152, v159
	v_sqrt_f32_e32 v159, v152
	v_lshlrev_b32_e32 v152, 16, v213
	v_and_b32_e32 v153, 0xffff0000, v213
	v_pk_mul_f32 v[152:153], v[154:155], v[152:153]
	v_and_b32_e32 v149, 0xffff0000, v214
	v_pk_mul_f32 v[152:153], v[152:153], v[158:159]
	v_pk_mul_f32 v[148:149], v[138:139], v[148:149]
	v_pk_fma_f32 v[136:137], v[136:137], v[156:157], v[152:153]
	v_cvt_pk_bf16_f32 v144, v148, v149
	v_lshlrev_b32_e32 v148, 16, v215
	v_and_b32_e32 v149, 0xffff0000, v215
	v_pk_mul_f32 v[148:149], v[136:137], v[148:149]
	s_nop 0
	v_cvt_pk_bf16_f32 v145, v148, v149
	global_store_dwordx2 v[146:147], v[144:145], off
	v_add_co_u32_e32 v144, vcc, s1, v140
	s_mov_b32 s1, 0x1ba0d000
	s_nop 0
	v_addc_co_u32_e32 v145, vcc, 0, v141, vcc
	s_nop 0
	s_nop 0
	v_lshlrev_b32_e32 v150, 16, v216
	v_and_b32_e32 v151, 0xffff0000, v216
	v_lshlrev_b32_e32 v154, 16, v217
	v_and_b32_e32 v155, 0xffff0000, v217
	v_lshlrev_b32_e32 v146, 16, v218
	v_and_b32_e32 v147, 0xffff0000, v218
	v_add_f32_e32 v144, v68, v150
	v_mul_f32_e32 v144, 0xbfb8aa3b, v144
	v_exp_f32_e32 v144, v144
	v_lshlrev_b32_e32 v156, 16, v219
	v_and_b32_e32 v157, 0xffff0000, v219
	v_and_b32_e32 v153, 0xffff0000, v222
	v_add_f32_e32 v144, 1.0, v144
	v_rcp_f32_e32 v145, v144
	v_add_f32_e32 v144, v64, v146
	v_mul_f32_e32 v144, 0xbfb8aa3b, v144
	v_exp_f32_e32 v144, v144
	v_mul_f32_e32 v145, v72, v145
	v_exp_f32_e32 v146, v145
	v_add_f32_e32 v144, 1.0, v144
	v_rcp_f32_e32 v144, v144
	v_sub_f32_e32 v145, 1.0, v146
	v_add_f32_e32 v150, 1.0, v146
	v_mul_f32_e32 v145, v145, v150
	v_sqrt_f32_e32 v150, v145
	v_add_f32_e32 v145, v69, v151
	v_mul_f32_e32 v145, 0xbfb8aa3b, v145
	v_exp_f32_e32 v145, v145
	s_nop 0
	v_add_f32_e32 v145, 1.0, v145
	v_rcp_f32_e32 v151, v145
	v_add_f32_e32 v145, v65, v147
	v_mul_f32_e32 v145, 0xbfb8aa3b, v145
	v_exp_f32_e32 v145, v145
	v_mul_f32_e32 v147, v73, v151
	v_exp_f32_e32 v147, v147
	v_add_f32_e32 v145, 1.0, v145
	v_rcp_f32_e32 v145, v145
	v_sub_f32_e32 v151, 1.0, v147
	v_add_f32_e32 v152, 1.0, v147
	v_mul_f32_e32 v151, v151, v152
	v_sqrt_f32_e32 v151, v151
	v_lshlrev_b32_e32 v152, 16, v222
	v_pk_mul_f32 v[144:145], v[144:145], v[152:153]
	v_add_f32_e32 v148, v70, v154
	v_pk_mul_f32 v[144:145], v[144:145], v[150:151]
	v_mul_f32_e32 v148, 0xbfb8aa3b, v148
	v_pk_fma_f32 v[138:139], v[138:139], v[146:147], v[144:145]
	v_add_co_u32_e32 v144, vcc, s1, v140
	v_exp_f32_e32 v148, v148
	s_nop 0
	v_addc_co_u32_e32 v145, vcc, 0, v141, vcc
	v_add_f32_e32 v148, 1.0, v148
	v_rcp_f32_e32 v148, v148
	v_add_f32_e32 v150, v66, v156
	v_mul_f32_e32 v150, 0xbfb8aa3b, v150
	v_exp_f32_e32 v150, v150
	v_mul_f32_e32 v148, v74, v148
	v_exp_f32_e32 v152, v148
	s_mov_b32 s1, 0x21a06000
	v_add_f32_e32 v150, 1.0, v150
	v_rcp_f32_e32 v150, v150
	v_sub_f32_e32 v148, 1.0, v152
	v_add_f32_e32 v151, 1.0, v152
	v_mul_f32_e32 v148, v148, v151
	v_sqrt_f32_e32 v154, v148
	v_add_f32_e32 v148, v71, v155
	v_mul_f32_e32 v148, 0xbfb8aa3b, v148
	v_exp_f32_e32 v148, v148
	v_add_f32_e32 v151, v67, v157
	v_mul_f32_e32 v151, 0xbfb8aa3b, v151
	v_exp_f32_e32 v151, v151
	v_add_f32_e32 v148, 1.0, v148
	v_rcp_f32_e32 v148, v148
	v_add_f32_e32 v151, 1.0, v151
	v_rcp_f32_e32 v151, v151
	v_mul_f32_e32 v148, v75, v148
	v_exp_f32_e32 v153, v148
	v_lshlrev_b32_e32 v146, 16, v224
	v_sub_f32_e32 v148, 1.0, v153
	v_add_f32_e32 v155, 1.0, v153
	v_mul_f32_e32 v148, v148, v155
	v_sqrt_f32_e32 v155, v148
	v_lshlrev_b32_e32 v148, 16, v223
	v_and_b32_e32 v149, 0xffff0000, v223
	v_pk_mul_f32 v[148:149], v[150:151], v[148:149]
	v_and_b32_e32 v147, 0xffff0000, v224
	v_pk_mul_f32 v[148:149], v[148:149], v[154:155]
	v_pk_mul_f32 v[146:147], v[138:139], v[146:147]
	v_pk_fma_f32 v[136:137], v[136:137], v[152:153], v[148:149]
	v_cvt_pk_bf16_f32 v144, v146, v147
	v_lshlrev_b32_e32 v146, 16, v225
	v_and_b32_e32 v147, 0xffff0000, v225
	v_pk_mul_f32 v[146:147], v[136:137], v[146:147]
	s_nop 0
	v_cvt_pk_bf16_f32 v145, v146, v147
	v_add_co_u32_e32 v146, vcc, s1, v142
	s_mov_b32 s1, 0x23a0f000
	s_nop 0
	v_addc_co_u32_e32 v147, vcc, 0, v143, vcc
	global_store_dwordx2 v[146:147], v[144:145], off
	v_add_co_u32_e32 v144, vcc, s1, v140
	s_mov_b32 s1, 0x1fa07000
	s_nop 0
	v_addc_co_u32_e32 v145, vcc, 0, v141, vcc
	s_nop 0
	v_add_co_u32_e32 v148, vcc, s1, v142
	s_mov_b32 s1, 0x1ba0f000
	s_nop 0
	v_addc_co_u32_e32 v149, vcc, 0, v143, vcc
	v_add_co_u32_e32 v140, vcc, s1, v140
	v_lshlrev_b32_e32 v150, 16, v226
	v_addc_co_u32_e32 v141, vcc, 0, v141, vcc
	v_and_b32_e32 v151, 0xffff0000, v226
	v_lshlrev_b32_e32 v154, 16, v227
	v_and_b32_e32 v155, 0xffff0000, v227
	v_lshlrev_b32_e32 v146, 16, v232
	v_and_b32_e32 v147, 0xffff0000, v232
	v_add_f32_e32 v144, v68, v150
	v_mul_f32_e32 v144, 0xbfb8aa3b, v144
	v_exp_f32_e32 v144, v144
	v_lshlrev_b32_e32 v156, 16, v233
	v_and_b32_e32 v157, 0xffff0000, v233
	v_and_b32_e32 v153, 0xffff0000, v234
	v_add_f32_e32 v144, 1.0, v144
	v_rcp_f32_e32 v145, v144
	v_add_f32_e32 v144, v64, v146
	v_mul_f32_e32 v144, 0xbfb8aa3b, v144
	v_exp_f32_e32 v144, v144
	v_mul_f32_e32 v145, v72, v145
	v_exp_f32_e32 v146, v145
	v_add_co_u32_e32 v142, vcc, 0x21a07000, v142
	v_add_f32_e32 v144, 1.0, v144
	v_sub_f32_e32 v145, 1.0, v146
	v_add_f32_e32 v150, 1.0, v146
	v_mul_f32_e32 v145, v145, v150
	v_sqrt_f32_e32 v150, v145
	v_add_f32_e32 v145, v69, v151
	v_mul_f32_e32 v145, 0xbfb8aa3b, v145
	v_exp_f32_e32 v145, v145
	v_rcp_f32_e32 v144, v144
	v_addc_co_u32_e32 v143, vcc, 0, v143, vcc
	v_add_f32_e32 v145, 1.0, v145
	v_rcp_f32_e32 v151, v145
	v_add_f32_e32 v145, v65, v147
	v_mul_f32_e32 v145, 0xbfb8aa3b, v145
	v_exp_f32_e32 v145, v145
	v_mul_f32_e32 v147, v73, v151
	v_exp_f32_e32 v147, v147
	v_add_f32_e32 v145, 1.0, v145
	v_rcp_f32_e32 v145, v145
	v_sub_f32_e32 v151, 1.0, v147
	v_add_f32_e32 v152, 1.0, v147
	v_mul_f32_e32 v151, v151, v152
	v_lshlrev_b32_e32 v152, 16, v234
	v_add_f32_e32 v148, v70, v154
	v_mul_f32_e32 v148, 0xbfb8aa3b, v148
	v_exp_f32_e32 v148, v148
	v_sqrt_f32_e32 v151, v151
	v_pk_mul_f32 v[144:145], v[144:145], v[152:153]
	v_add_f32_e32 v148, 1.0, v148
	v_rcp_f32_e32 v148, v148
	v_pk_mul_f32 v[144:145], v[144:145], v[150:151]
	v_add_f32_e32 v150, v66, v156
	v_mul_f32_e32 v150, 0xbfb8aa3b, v150
	v_mul_f32_e32 v148, v74, v148
	v_exp_f32_e32 v152, v148
	v_exp_f32_e32 v150, v150
	v_pk_fma_f32 v[138:139], v[138:139], v[146:147], v[144:145]
	v_sub_f32_e32 v148, 1.0, v152
	v_add_f32_e32 v151, 1.0, v152
	v_mul_f32_e32 v148, v148, v151
	v_sqrt_f32_e32 v154, v148
	v_add_f32_e32 v148, v71, v155
	v_mul_f32_e32 v148, 0xbfb8aa3b, v148
	v_exp_f32_e32 v148, v148
	v_add_f32_e32 v151, v67, v157
	v_mul_f32_e32 v151, 0xbfb8aa3b, v151
	v_exp_f32_e32 v151, v151
	v_add_f32_e32 v148, 1.0, v148
	v_rcp_f32_e32 v148, v148
	v_add_f32_e32 v150, 1.0, v150
	v_add_f32_e32 v151, 1.0, v151
	v_rcp_f32_e32 v150, v150
	v_mul_f32_e32 v148, v75, v148
	v_exp_f32_e32 v153, v148
	v_rcp_f32_e32 v151, v151
	v_lshlrev_b32_e32 v144, 16, v238
	v_and_b32_e32 v145, 0xffff0000, v238
	v_sub_f32_e32 v148, 1.0, v153
	v_add_f32_e32 v155, 1.0, v153
	v_mul_f32_e32 v148, v148, v155
	v_sqrt_f32_e32 v155, v148
	v_lshlrev_b32_e32 v148, 16, v235
	v_and_b32_e32 v149, 0xffff0000, v235
	v_pk_mul_f32 v[148:149], v[150:151], v[148:149]
	v_pk_mul_f32 v[144:145], v[138:139], v[144:145]
	v_pk_mul_f32 v[148:149], v[148:149], v[154:155]
	v_cvt_pk_bf16_f32 v140, v144, v145
	v_pk_fma_f32 v[136:137], v[136:137], v[152:153], v[148:149]
	v_lshlrev_b32_e32 v144, 16, v239
	v_and_b32_e32 v145, 0xffff0000, v239
	v_pk_mul_f32 v[144:145], v[136:137], v[144:145]
	s_nop 0
	v_cvt_pk_bf16_f32 v141, v144, v145
	global_store_dwordx2 v[142:143], v[140:141], off
	s_cbranch_scc0 .LBB0_1021
	v_add_u32_e32 v192, s96, v192
	s_mov_b32 s0, 0x1ffff
	v_cmp_lt_i32_e32 vcc, s0, v192
	v_mov_b64_e32 v[134:135], v[130:131]
	v_mov_b64_e32 v[138:139], v[122:123]
	v_mov_b64_e32 v[142:143], v[114:115]
	v_mov_b64_e32 v[150:151], v[106:107]
	v_mov_b64_e32 v[158:159], v[98:99]
	v_mov_b64_e32 v[166:167], v[90:91]
	v_mov_b64_e32 v[146:147], v[126:127]
	v_mov_b64_e32 v[154:155], v[118:119]
	v_mov_b64_e32 v[162:163], v[110:111]
	v_mov_b64_e32 v[170:171], v[102:103]
	v_mov_b64_e32 v[174:175], v[94:95]
	v_mov_b64_e32 v[178:179], v[86:87]
	v_add_u32_e32 v193, s2, v193
	s_or_b64 s[92:93], vcc, s[92:93]
	v_mov_b64_e32 v[132:133], v[128:129]
	v_mov_b64_e32 v[136:137], v[120:121]
	v_mov_b64_e32 v[140:141], v[112:113]
	v_mov_b64_e32 v[148:149], v[104:105]
	v_mov_b64_e32 v[156:157], v[96:97]
	v_mov_b64_e32 v[164:165], v[88:89]
	v_mov_b64_e32 v[144:145], v[124:125]
	v_mov_b64_e32 v[152:153], v[116:117]
	v_mov_b64_e32 v[160:161], v[108:109]
	v_mov_b64_e32 v[168:169], v[100:101]
	v_mov_b64_e32 v[172:173], v[92:93]
	v_mov_b64_e32 v[176:177], v[84:85]
	s_andn2_b64 exec, exec, s[92:93]
	s_cbranch_execnz .LBB0_976
